# K-loop first iteration after an epilogue: super-phase 1/2 waits relaxed by the 8+ queued epilogue stores (vmcnt retires in order), stores drain until super-phase 3
# baseline (speedup 1.0000x reference)
.LBB0_225:
	s_add_i32 m0, s68, 0x18000
	v_lshl_add_u64 v[0:1], v[0:1], 0, s[50:51]
	s_waitcnt vmcnt(2)
	s_barrier
	global_load_lds_dwordx4 v[0:1], off
	v_lshl_add_u64 v[0:1], v[2:3], 0, s[50:51]
	s_add_i32 m0, s68, 0x1a000
	s_add_i32 s64, s68, 0x8000
	global_load_lds_dwordx4 v[0:1], off
	v_lshl_add_u64 v[0:1], v[8:9], 0, s[50:51]
	s_mov_b32 m0, s64
	s_add_i32 s65, s68, 0xa000
	global_load_lds_dwordx4 v[0:1], off
	v_lshl_add_u64 v[0:1], v[10:11], 0, s[50:51]
	s_mov_b32 m0, s65
	v_lshrrev_b32_e32 v19, 1, v18
	global_load_lds_dwordx4 v[0:1], off
	s_add_i32 m0, s68, 0x1c000
	v_lshl_add_u64 v[0:1], v[4:5], 0, s[50:51]
	global_load_lds_dwordx4 v[0:1], off
	v_lshl_add_u64 v[0:1], v[6:7], 0, s[50:51]
	s_add_i32 m0, s68, 0x1e000
	s_lshl_b32 s4, s4, 5
	global_load_lds_dwordx4 v[0:1], off
	v_and_b32_e32 v154, 24, v19
	s_and_b32 s81, s4, 0x60
	v_or_b32_e32 v156, s81, v154
	v_lshlrev_b32_e32 v1, 6, v156
	v_and_b32_e32 v184, 0x1c00, v1
	v_or_b32_e32 v1, 0x80, v156
	v_lshlrev_b32_e32 v2, 6, v1
	v_lshrrev_b32_e32 v187, 4, v1
	v_cvt_f32_u32_e32 v1, s12
	v_and_b32_e32 v155, 15, v18
	v_lshlrev_b32_e32 v20, 1, v154
	v_lshlrev_b32_e32 v18, 2, v18
	v_rcp_iflag_f32_e32 v1, v1
	s_lshl_b32 s73, s5, 6
	v_lshl_or_b32 v20, v155, 6, v20
	s_lshl_b32 s5, s5, 13
	v_and_b32_e32 v18, 32, v18
	s_lshl_b32 s4, s81, 7
	v_mul_f32_e32 v1, 0x4f7ffffe, v1
	v_bitop3_b32 v21, v20, s5, v18 bitop3:0xde
	v_bitop3_b32 v157, s4, v20, v18 bitop3:0xf6
	v_readlane_b32 s4, v255, 5
	v_cvt_u32_f32_e32 v1, v1
	s_lshr_b32 s55, s8, 6
	v_and_b32_e32 v0, 8, v19
	v_lshlrev_b32_e32 v144, 5, v155
	v_readlane_b32 s5, v255, 6
	s_add_i32 s72, s55, -2
	v_and_b32_e32 v185, 0x3c00, v2
	v_lshl_add_u64 v[2:3], s[4:5], 0, v[144:145]
	v_lshlrev_b32_e32 v144, 1, v0
	s_cmpk_lt_u32 s26, 0x100
	v_lshl_add_u64 v[158:159], v[2:3], 0, v[144:145]
	v_lshlrev_b32_e32 v144, 2, v0
	s_cselect_b64 s[86:87], -1, 0
	v_lshl_add_u64 v[160:161], s[0:1], 0, v[144:145]
	s_sub_i32 s0, 0, s12
	v_readfirstlane_b32 s1, v1
	v_add_u32_e32 v1, v14, v12
	s_waitcnt vmcnt(6)
	s_mul_i32 s0, s0, s1
	v_add_lshl_u32 v144, v1, v13, 1
	v_add_u32_e32 v1, v17, v15
	s_mul_hi_u32 s0, s1, s0
	v_lshl_add_u64 v[162:163], s[48:49], 0, v[144:145]
	v_add_lshl_u32 v144, v1, v16, 1
	v_lshrrev_b32_e32 v186, 4, v156
	s_ashr_i32 s82, s80, 31
	s_mov_b32 s35, s27
	s_lshr_b32 s83, s34, 3
	s_mov_b32 s60, 0
	s_add_i32 s52, s1, s0
	v_lshl_add_u64 v[164:165], s[48:49], 0, v[144:145]
	v_add_u32_e32 v188, 0, v21
	v_lshlrev_b32_e32 v166, 1, v0
	s_mov_b32 s49, 0
	s_barrier
	s_mov_b32 s98, 0
	s_branch .LBB0_228
.Lsw1_r:
	s_waitcnt vmcnt(16)
	s_branch .Lsw1_j
.Lsw2_r:
	s_waitcnt vmcnt(16)
	s_mov_b32 s98, 0
	s_branch .Lsw2_j
.LBB0_226:
	s_mov_b32 s98, 1
	s_mov_b64 s[4:5], 0

.LBB0_246:
	s_add_i32 s90, s42, 2
	s_add_u32 s91, s6, 0x80
	s_addc_u32 s43, s7, 0
	s_cmp_eq_u32 s72, s42
	s_cselect_b32 s43, s89, s43
	s_cselect_b32 s42, s88, s91
	s_cselect_b32 s93, s1, s66
	s_cselect_b32 s92, s0, s8
	ds_read_b128 v[128:131], v222
	ds_read_b128 v[132:135], v222 offset:1024
	ds_read_b128 v[136:139], v222 offset:2048
	ds_read_b128 v[140:143], v222 offset:3072
	ds_read_b128 v[168:171], v222 offset:16384
	ds_read_b128 v[172:175], v222 offset:17408
	ds_read_b128 v[176:179], v222 offset:18432
	ds_read_b128 v[180:183], v222 offset:19456
	s_add_i32 m0, s68, 0xc000
	ds_read_b128 v[190:193], v188
	ds_read_b128 v[194:197], v188 offset:1024
	ds_read_b128 v[198:201], v188 offset:2048
	ds_read_b128 v[202:205], v188 offset:3072
	ds_read_b128 v[206:209], v188 offset:4096
	ds_read_b128 v[210:213], v188 offset:5120
	ds_read_b128 v[214:217], v188 offset:6144
	ds_read_b128 v[218:221], v188 offset:7168
	global_load_lds_dwordx4 v162, s[6:7]
	s_add_i32 m0, s68, 0xe000
	s_nop 0
	global_load_lds_dwordx4 v164, s[6:7]
	s_cmp_lg_u32 s98, 0
	s_cbranch_scc1 .Lsw1_r
	s_waitcnt vmcnt(8)
.Lsw1_j:
	s_waitcnt lgkmcnt(0)
	s_barrier
	s_setprio 1
	s_waitcnt lgkmcnt(0)
	v_mfma_f32_16x16x32_bf16 v[124:127], v[128:131], v[190:193], v[124:127]
	v_mfma_f32_16x16x32_bf16 v[120:123], v[136:139], v[190:193], v[120:123]
	v_mfma_f32_16x16x32_bf16 v[116:119], v[128:131], v[198:201], v[116:119]
	v_mfma_f32_16x16x32_bf16 v[112:115], v[136:139], v[198:201], v[112:115]
	v_mfma_f32_16x16x32_bf16 v[100:103], v[128:131], v[206:209], v[100:103]
	v_mfma_f32_16x16x32_bf16 v[96:99], v[136:139], v[206:209], v[96:99]
	v_mfma_f32_16x16x32_bf16 v[84:87], v[128:131], v[214:217], v[84:87]
	v_mfma_f32_16x16x32_bf16 v[80:83], v[136:139], v[214:217], v[80:83]
	v_mfma_f32_16x16x32_bf16 v[124:127], v[132:135], v[194:197], v[124:127]
	v_mfma_f32_16x16x32_bf16 v[120:123], v[140:143], v[194:197], v[120:123]
	v_mfma_f32_16x16x32_bf16 v[116:119], v[132:135], v[202:205], v[116:119]
	v_mfma_f32_16x16x32_bf16 v[112:115], v[140:143], v[202:205], v[112:115]
	v_mfma_f32_16x16x32_bf16 v[100:103], v[132:135], v[210:213], v[100:103]
	v_mfma_f32_16x16x32_bf16 v[96:99], v[140:143], v[210:213], v[96:99]
	v_mfma_f32_16x16x32_bf16 v[84:87], v[132:135], v[218:221], v[84:87]
	v_mfma_f32_16x16x32_bf16 v[80:83], v[140:143], v[218:221], v[80:83]
	s_setprio 0
	s_setprio 1
	v_mfma_f32_16x16x32_bf16 v[108:111], v[168:171], v[190:193], v[108:111]
	v_mfma_f32_16x16x32_bf16 v[104:107], v[176:179], v[190:193], v[104:107]
	v_mfma_f32_16x16x32_bf16 v[92:95], v[168:171], v[198:201], v[92:95]
	v_mfma_f32_16x16x32_bf16 v[88:91], v[176:179], v[198:201], v[88:91]
	v_mfma_f32_16x16x32_bf16 v[76:79], v[168:171], v[206:209], v[76:79]
	v_mfma_f32_16x16x32_bf16 v[72:75], v[176:179], v[206:209], v[72:75]
	v_mfma_f32_16x16x32_bf16 v[68:71], v[168:171], v[214:217], v[68:71]
	v_mfma_f32_16x16x32_bf16 v[64:67], v[176:179], v[214:217], v[64:67]
	v_mfma_f32_16x16x32_bf16 v[108:111], v[172:175], v[194:197], v[108:111]
	v_mfma_f32_16x16x32_bf16 v[104:107], v[180:183], v[194:197], v[104:107]
	v_mfma_f32_16x16x32_bf16 v[92:95], v[172:175], v[202:205], v[92:95]
	v_mfma_f32_16x16x32_bf16 v[88:91], v[180:183], v[202:205], v[88:91]
	v_mfma_f32_16x16x32_bf16 v[76:79], v[172:175], v[210:213], v[76:79]
	v_mfma_f32_16x16x32_bf16 v[72:75], v[180:183], v[210:213], v[72:75]
	v_mfma_f32_16x16x32_bf16 v[68:71], v[172:175], v[218:221], v[68:71]
	v_mfma_f32_16x16x32_bf16 v[64:67], v[180:183], v[218:221], v[64:67]
	s_setprio 0
	s_barrier
	s_add_i32 m0, s15, 0x10000
	ds_read_b128 v[190:193], v188 offset:16384
	ds_read_b128 v[194:197], v188 offset:17408
	ds_read_b128 v[198:201], v188 offset:18432
	ds_read_b128 v[202:205], v188 offset:19456
	ds_read_b128 v[206:209], v188 offset:20480
	ds_read_b128 v[210:213], v188 offset:21504
	ds_read_b128 v[214:217], v188 offset:22528
	ds_read_b128 v[218:221], v188 offset:23552
	global_load_lds_dwordx4 v148, s[92:93]
	s_add_i32 m0, s15, 0x12000
	s_nop 0
	global_load_lds_dwordx4 v152, s[92:93]
	s_add_i32 m0, s15, 0x14000
	s_add_u32 s92, s92, s21
	s_addc_u32 s93, s93, 0
	global_load_lds_dwordx4 v148, s[92:93]
	s_add_i32 m0, s15, 0x16000
	s_nop 0
	global_load_lds_dwordx4 v152, s[92:93]
	s_mov_b32 m0, s68
	s_nop 0
	global_load_lds_dwordx4 v146, s[42:43]
	s_mov_b32 m0, s23
	s_nop 0
	global_load_lds_dwordx4 v150, s[42:43]
	s_cmp_lg_u32 s98, 0
	s_cbranch_scc1 .Lsw2_r
	s_waitcnt vmcnt(8)
.Lsw2_j:
	s_waitcnt lgkmcnt(0)
	s_barrier
	s_setprio 1
	s_waitcnt lgkmcnt(0)
	v_mfma_f32_16x16x32_bf16 v[60:63], v[128:131], v[190:193], v[60:63]
	v_mfma_f32_16x16x32_bf16 v[56:59], v[136:139], v[190:193], v[56:59]
	v_mfma_f32_16x16x32_bf16 v[52:55], v[128:131], v[198:201], v[52:55]
	v_mfma_f32_16x16x32_bf16 v[48:51], v[136:139], v[198:201], v[48:51]
	v_mfma_f32_16x16x32_bf16 v[36:39], v[128:131], v[206:209], v[36:39]
	v_mfma_f32_16x16x32_bf16 v[32:35], v[136:139], v[206:209], v[32:35]
	v_mfma_f32_16x16x32_bf16 v[20:23], v[128:131], v[214:217], v[20:23]
	v_mfma_f32_16x16x32_bf16 v[16:19], v[136:139], v[214:217], v[16:19]
	v_mfma_f32_16x16x32_bf16 v[60:63], v[132:135], v[194:197], v[60:63]
	v_mfma_f32_16x16x32_bf16 v[56:59], v[140:143], v[194:197], v[56:59]
	v_mfma_f32_16x16x32_bf16 v[52:55], v[132:135], v[202:205], v[52:55]
	v_mfma_f32_16x16x32_bf16 v[48:51], v[140:143], v[202:205], v[48:51]
	v_mfma_f32_16x16x32_bf16 v[36:39], v[132:135], v[210:213], v[36:39]
	v_mfma_f32_16x16x32_bf16 v[32:35], v[140:143], v[210:213], v[32:35]
	v_mfma_f32_16x16x32_bf16 v[20:23], v[132:135], v[218:221], v[20:23]
	v_mfma_f32_16x16x32_bf16 v[16:19], v[140:143], v[218:221], v[16:19]
	s_setprio 0
	s_setprio 1
	v_mfma_f32_16x16x32_bf16 v[44:47], v[168:171], v[190:193], v[44:47]
	v_mfma_f32_16x16x32_bf16 v[40:43], v[176:179], v[190:193], v[40:43]
	v_mfma_f32_16x16x32_bf16 v[28:31], v[168:171], v[198:201], v[28:31]
	v_mfma_f32_16x16x32_bf16 v[24:27], v[176:179], v[198:201], v[24:27]
	v_mfma_f32_16x16x32_bf16 v[12:15], v[168:171], v[206:209], v[12:15]
	v_mfma_f32_16x16x32_bf16 v[8:11], v[176:179], v[206:209], v[8:11]
	v_mfma_f32_16x16x32_bf16 v[4:7], v[168:171], v[214:217], v[4:7]
	v_mfma_f32_16x16x32_bf16 v[0:3], v[176:179], v[214:217], v[0:3]
	v_mfma_f32_16x16x32_bf16 v[44:47], v[172:175], v[194:197], v[44:47]
	v_mfma_f32_16x16x32_bf16 v[40:43], v[180:183], v[194:197], v[40:43]
	v_mfma_f32_16x16x32_bf16 v[28:31], v[172:175], v[202:205], v[28:31]
	v_mfma_f32_16x16x32_bf16 v[24:27], v[180:183], v[202:205], v[24:27]
	v_mfma_f32_16x16x32_bf16 v[12:15], v[172:175], v[210:213], v[12:15]
	v_mfma_f32_16x16x32_bf16 v[8:11], v[180:183], v[210:213], v[8:11]
	v_mfma_f32_16x16x32_bf16 v[4:7], v[172:175], v[218:221], v[4:7]
	v_mfma_f32_16x16x32_bf16 v[0:3], v[180:183], v[218:221], v[0:3]
	s_setprio 0
	s_barrier
	ds_read_b128 v[128:131], v222 offset:32768
	ds_read_b128 v[132:135], v222 offset:33792
	ds_read_b128 v[136:139], v222 offset:34816
	ds_read_b128 v[140:143], v222 offset:35840
	ds_read_b128 v[168:171], v222 offset:49152
	ds_read_b128 v[172:175], v222 offset:50176
	ds_read_b128 v[176:179], v222 offset:51200
	ds_read_b128 v[180:183], v222 offset:52224
	s_add_u32 s42, s42, s48
	s_addc_u32 s43, s43, 0
	s_mov_b32 m0, s40
	ds_read_b128 v[190:193], v188 offset:32768
	ds_read_b128 v[194:197], v188 offset:33792
	ds_read_b128 v[198:201], v188 offset:34816
	ds_read_b128 v[202:205], v188 offset:35840
	ds_read_b128 v[206:209], v188 offset:36864
	ds_read_b128 v[210:213], v188 offset:37888
	ds_read_b128 v[214:217], v188 offset:38912
	ds_read_b128 v[218:221], v188 offset:39936
	global_load_lds_dwordx4 v146, s[42:43]
	s_mov_b32 m0, s41
	s_nop 0
	global_load_lds_dwordx4 v150, s[42:43]
	s_waitcnt vmcnt(8)
	s_waitcnt lgkmcnt(0)
	s_barrier
	s_setprio 1
	s_waitcnt lgkmcnt(0)
	v_mfma_f32_16x16x32_bf16 v[124:127], v[128:131], v[190:193], v[124:127]
	v_mfma_f32_16x16x32_bf16 v[120:123], v[136:139], v[190:193], v[120:123]
	v_mfma_f32_16x16x32_bf16 v[116:119], v[128:131], v[198:201], v[116:119]
	v_mfma_f32_16x16x32_bf16 v[112:115], v[136:139], v[198:201], v[112:115]
	v_mfma_f32_16x16x32_bf16 v[100:103], v[128:131], v[206:209], v[100:103]
	v_mfma_f32_16x16x32_bf16 v[96:99], v[136:139], v[206:209], v[96:99]
	v_mfma_f32_16x16x32_bf16 v[84:87], v[128:131], v[214:217], v[84:87]
	v_mfma_f32_16x16x32_bf16 v[80:83], v[136:139], v[214:217], v[80:83]
	v_mfma_f32_16x16x32_bf16 v[124:127], v[132:135], v[194:197], v[124:127]
	v_mfma_f32_16x16x32_bf16 v[120:123], v[140:143], v[194:197], v[120:123]
	v_mfma_f32_16x16x32_bf16 v[116:119], v[132:135], v[202:205], v[116:119]
	v_mfma_f32_16x16x32_bf16 v[112:115], v[140:143], v[202:205], v[112:115]
	v_mfma_f32_16x16x32_bf16 v[100:103], v[132:135], v[210:213], v[100:103]
	v_mfma_f32_16x16x32_bf16 v[96:99], v[140:143], v[210:213], v[96:99]
	v_mfma_f32_16x16x32_bf16 v[84:87], v[132:135], v[218:221], v[84:87]
	v_mfma_f32_16x16x32_bf16 v[80:83], v[140:143], v[218:221], v[80:83]
	s_setprio 0
	s_setprio 1
	v_mfma_f32_16x16x32_bf16 v[108:111], v[168:171], v[190:193], v[108:111]
	v_mfma_f32_16x16x32_bf16 v[104:107], v[176:179], v[190:193], v[104:107]
	v_mfma_f32_16x16x32_bf16 v[92:95], v[168:171], v[198:201], v[92:95]
	v_mfma_f32_16x16x32_bf16 v[88:91], v[176:179], v[198:201], v[88:91]
	v_mfma_f32_16x16x32_bf16 v[76:79], v[168:171], v[206:209], v[76:79]
	v_mfma_f32_16x16x32_bf16 v[72:75], v[176:179], v[206:209], v[72:75]
	v_mfma_f32_16x16x32_bf16 v[68:71], v[168:171], v[214:217], v[68:71]
	v_mfma_f32_16x16x32_bf16 v[64:67], v[176:179], v[214:217], v[64:67]
	v_mfma_f32_16x16x32_bf16 v[108:111], v[172:175], v[194:197], v[108:111]
	v_mfma_f32_16x16x32_bf16 v[104:107], v[180:183], v[194:197], v[104:107]
	v_mfma_f32_16x16x32_bf16 v[92:95], v[172:175], v[202:205], v[92:95]
	v_mfma_f32_16x16x32_bf16 v[88:91], v[180:183], v[202:205], v[88:91]
	v_mfma_f32_16x16x32_bf16 v[76:79], v[172:175], v[210:213], v[76:79]
	v_mfma_f32_16x16x32_bf16 v[72:75], v[180:183], v[210:213], v[72:75]
	v_mfma_f32_16x16x32_bf16 v[68:71], v[172:175], v[218:221], v[68:71]
	v_mfma_f32_16x16x32_bf16 v[64:67], v[180:183], v[218:221], v[64:67]
	s_setprio 0
	s_barrier
	s_sub_u32 s92, s92, s21
	s_subb_u32 s93, s93, 0
	s_add_i32 m0, s15, 0x17f80
	ds_read_b128 v[190:193], v188 offset:49152
	ds_read_b128 v[194:197], v188 offset:50176
	ds_read_b128 v[198:201], v188 offset:51200
	ds_read_b128 v[202:205], v188 offset:52224
	ds_read_b128 v[206:209], v188 offset:53248
	ds_read_b128 v[210:213], v188 offset:54272
	ds_read_b128 v[214:217], v188 offset:55296
	ds_read_b128 v[218:221], v188 offset:56320
	global_load_lds_dwordx4 v148, s[92:93] offset:128
	s_add_i32 m0, s15, 0x19f80
	s_nop 0
	global_load_lds_dwordx4 v152, s[92:93] offset:128
	s_add_u32 s92, s92, s21
	s_addc_u32 s93, s93, 0
	s_add_i32 m0, s15, 0x1bf80
	s_add_u32 s6, s6, 0x100
	s_addc_u32 s7, s7, 0
	global_load_lds_dwordx4 v148, s[92:93] offset:128
	s_add_i32 m0, s15, 0x1df80
	s_sub_u32 s42, s42, s48
	s_subb_u32 s43, s43, 0
	global_load_lds_dwordx4 v152, s[92:93] offset:128
	s_add_i32 m0, s64, 0xffffff80
	s_add_u32 s8, s8, 0x100
	s_addc_u32 s66, s66, 0
	global_load_lds_dwordx4 v146, s[42:43] offset:128
	s_add_i32 m0, s65, 0xffffff80
	s_nop 0
	global_load_lds_dwordx4 v150, s[42:43] offset:128
	s_waitcnt vmcnt(8)
	s_waitcnt lgkmcnt(0)
	s_barrier
	s_setprio 1
	s_waitcnt lgkmcnt(0)
	v_mfma_f32_16x16x32_bf16 v[60:63], v[128:131], v[190:193], v[60:63]
	v_mfma_f32_16x16x32_bf16 v[56:59], v[136:139], v[190:193], v[56:59]
	v_mfma_f32_16x16x32_bf16 v[52:55], v[128:131], v[198:201], v[52:55]
	v_mfma_f32_16x16x32_bf16 v[48:51], v[136:139], v[198:201], v[48:51]
	v_mfma_f32_16x16x32_bf16 v[36:39], v[128:131], v[206:209], v[36:39]
	v_mfma_f32_16x16x32_bf16 v[32:35], v[136:139], v[206:209], v[32:35]
	v_mfma_f32_16x16x32_bf16 v[20:23], v[128:131], v[214:217], v[20:23]
	v_mfma_f32_16x16x32_bf16 v[16:19], v[136:139], v[214:217], v[16:19]
	v_mfma_f32_16x16x32_bf16 v[60:63], v[132:135], v[194:197], v[60:63]
	v_mfma_f32_16x16x32_bf16 v[56:59], v[140:143], v[194:197], v[56:59]
	v_mfma_f32_16x16x32_bf16 v[52:55], v[132:135], v[202:205], v[52:55]
	v_mfma_f32_16x16x32_bf16 v[48:51], v[140:143], v[202:205], v[48:51]
	v_mfma_f32_16x16x32_bf16 v[36:39], v[132:135], v[210:213], v[36:39]
	v_mfma_f32_16x16x32_bf16 v[32:35], v[140:143], v[210:213], v[32:35]
	v_mfma_f32_16x16x32_bf16 v[20:23], v[132:135], v[218:221], v[20:23]
	v_mfma_f32_16x16x32_bf16 v[16:19], v[140:143], v[218:221], v[16:19]
	s_setprio 0
	s_setprio 1
	v_mfma_f32_16x16x32_bf16 v[44:47], v[168:171], v[190:193], v[44:47]
	v_mfma_f32_16x16x32_bf16 v[40:43], v[176:179], v[190:193], v[40:43]
	v_mfma_f32_16x16x32_bf16 v[28:31], v[168:171], v[198:201], v[28:31]
	v_mfma_f32_16x16x32_bf16 v[24:27], v[176:179], v[198:201], v[24:27]
	v_mfma_f32_16x16x32_bf16 v[12:15], v[168:171], v[206:209], v[12:15]
	v_mfma_f32_16x16x32_bf16 v[8:11], v[176:179], v[206:209], v[8:11]
	v_mfma_f32_16x16x32_bf16 v[4:7], v[168:171], v[214:217], v[4:7]
	v_mfma_f32_16x16x32_bf16 v[0:3], v[176:179], v[214:217], v[0:3]
	v_mfma_f32_16x16x32_bf16 v[44:47], v[172:175], v[194:197], v[44:47]
	v_mfma_f32_16x16x32_bf16 v[40:43], v[180:183], v[194:197], v[40:43]
	v_mfma_f32_16x16x32_bf16 v[28:31], v[172:175], v[202:205], v[28:31]
	v_mfma_f32_16x16x32_bf16 v[24:27], v[180:183], v[202:205], v[24:27]
	v_mfma_f32_16x16x32_bf16 v[12:15], v[172:175], v[210:213], v[12:15]
	v_mfma_f32_16x16x32_bf16 v[8:11], v[180:183], v[210:213], v[8:11]
	v_mfma_f32_16x16x32_bf16 v[4:7], v[172:175], v[218:221], v[4:7]
	v_mfma_f32_16x16x32_bf16 v[0:3], v[180:183], v[218:221], v[0:3]
	s_setprio 0
	s_barrier
	s_cmp_ge_u32 s90, s55
	s_mov_b32 s42, s90
	s_cbranch_scc0 .LBB0_246
	s_and_b64 vcc, exec, s[86:87]
	s_cbranch_vccz .LBB0_249
	s_barrier
